# accumulator re-zeroing per GEMM unit with 64 v_mov_b64 instead of 128 v_mov_b32
# speedup vs baseline: 1.0050x; 1.0031x over previous
.LBB0_169:
	s_ashr_i32 s45, s44, 31
	s_lshl_b64 s[34:35], s[44:45], 19
	s_add_u32 s46, s25, s34
	s_addc_u32 s47, s27, s35
	s_and_b64 s[34:35], s[4:5], exec
	s_cselect_b32 s7, s47, s51
	s_cselect_b32 s34, s46, s50
	s_ashr_i32 s43, s42, 31
	s_lshl_b64 s[48:49], s[42:43], 19
	s_add_u32 s48, s37, s48
	s_addc_u32 s49, s39, s49
	s_and_b64 s[54:55], s[4:5], exec
	s_cselect_b32 s35, s49, s53
	s_cselect_b32 s43, s48, s52
	s_add_u32 s50, s50, 0x40080
	s_addc_u32 s51, s51, 0
	s_add_u32 s33, s52, 0x100
	v_mov_b64_e32 v[0:1], 0
	s_addc_u32 s45, s53, 0
	s_mov_b32 s67, -2
	s_waitcnt lgkmcnt(0)
	v_mov_b64_e32 v[2:3], 0
	v_mov_b64_e32 v[4:5], 0
	v_mov_b64_e32 v[6:7], 0
	v_mov_b64_e32 v[16:17], 0
	v_mov_b64_e32 v[18:19], 0
	v_mov_b64_e32 v[20:21], 0
	v_mov_b64_e32 v[22:23], 0
	v_mov_b64_e32 v[32:33], 0
	v_mov_b64_e32 v[34:35], 0
	v_mov_b64_e32 v[36:37], 0
	v_mov_b64_e32 v[38:39], 0
	v_mov_b64_e32 v[48:49], 0
	v_mov_b64_e32 v[50:51], 0
	v_mov_b64_e32 v[52:53], 0
	v_mov_b64_e32 v[54:55], 0
	v_mov_b64_e32 v[8:9], 0
	v_mov_b64_e32 v[10:11], 0
	v_mov_b64_e32 v[12:13], 0
	v_mov_b64_e32 v[14:15], 0
	v_mov_b64_e32 v[24:25], 0
	v_mov_b64_e32 v[26:27], 0
	v_mov_b64_e32 v[28:29], 0
	v_mov_b64_e32 v[30:31], 0
	v_mov_b64_e32 v[40:41], 0
	v_mov_b64_e32 v[42:43], 0
	v_mov_b64_e32 v[44:45], 0
	v_mov_b64_e32 v[46:47], 0
	v_mov_b64_e32 v[56:57], 0
	v_mov_b64_e32 v[58:59], 0
	v_mov_b64_e32 v[60:61], 0
	v_mov_b64_e32 v[62:63], 0
	v_mov_b64_e32 v[64:65], 0
	v_mov_b64_e32 v[66:67], 0
	v_mov_b64_e32 v[68:69], 0
	v_mov_b64_e32 v[70:71], 0
	v_mov_b64_e32 v[80:81], 0
	v_mov_b64_e32 v[82:83], 0
	v_mov_b64_e32 v[84:85], 0
	v_mov_b64_e32 v[86:87], 0
	v_mov_b64_e32 v[96:97], 0
	v_mov_b64_e32 v[98:99], 0
	v_mov_b64_e32 v[100:101], 0
	v_mov_b64_e32 v[102:103], 0
	v_mov_b64_e32 v[112:113], 0
	v_mov_b64_e32 v[114:115], 0
	v_mov_b64_e32 v[116:117], 0
	v_mov_b64_e32 v[118:119], 0
	v_mov_b64_e32 v[72:73], 0
	v_mov_b64_e32 v[74:75], 0
	v_mov_b64_e32 v[76:77], 0
	v_mov_b64_e32 v[78:79], 0
	v_mov_b64_e32 v[88:89], 0
	v_mov_b64_e32 v[90:91], 0
	v_mov_b64_e32 v[92:93], 0
	v_mov_b64_e32 v[94:95], 0
	v_mov_b64_e32 v[104:105], 0
	v_mov_b64_e32 v[106:107], 0
	v_mov_b64_e32 v[108:109], 0
	v_mov_b64_e32 v[110:111], 0
	v_mov_b64_e32 v[120:121], 0
	v_mov_b64_e32 v[122:123], 0
	v_mov_b64_e32 v[124:125], 0
	v_mov_b64_e32 v[126:127], 0

.LBB0_390:
	s_cmp_lg_u32 s33, 0
	s_cselect_b64 s[46:47], -1, 0
	s_and_b64 s[34:35], s[46:47], exec
	s_cselect_b32 s34, s33, 48
	s_cmp_lt_i32 s34, 1
	s_cbranch_scc1 .LBB0_402
	s_add_i32 s33, s34, -2
	s_add_u32 s35, s50, 0x100
	v_mov_b64_e32 v[0:1], 0
	s_addc_u32 s91, s51, 0
	s_mov_b32 s52, 0
	v_mov_b64_e32 v[2:3], 0
	v_mov_b64_e32 v[4:5], 0
	v_mov_b64_e32 v[6:7], 0
	v_mov_b64_e32 v[16:17], 0
	v_mov_b64_e32 v[18:19], 0
	v_mov_b64_e32 v[20:21], 0
	v_mov_b64_e32 v[22:23], 0
	v_mov_b64_e32 v[32:33], 0
	v_mov_b64_e32 v[34:35], 0
	v_mov_b64_e32 v[36:37], 0
	v_mov_b64_e32 v[38:39], 0
	v_mov_b64_e32 v[48:49], 0
	v_mov_b64_e32 v[50:51], 0
	v_mov_b64_e32 v[52:53], 0
	v_mov_b64_e32 v[54:55], 0
	v_mov_b64_e32 v[8:9], 0
	v_mov_b64_e32 v[10:11], 0
	v_mov_b64_e32 v[12:13], 0
	v_mov_b64_e32 v[14:15], 0
	v_mov_b64_e32 v[24:25], 0
	v_mov_b64_e32 v[26:27], 0
	v_mov_b64_e32 v[28:29], 0
	v_mov_b64_e32 v[30:31], 0
	v_mov_b64_e32 v[40:41], 0
	v_mov_b64_e32 v[42:43], 0
	v_mov_b64_e32 v[44:45], 0
	v_mov_b64_e32 v[46:47], 0
	v_mov_b64_e32 v[56:57], 0
	v_mov_b64_e32 v[58:59], 0
	v_mov_b64_e32 v[60:61], 0
	v_mov_b64_e32 v[62:63], 0
	v_mov_b64_e32 v[64:65], 0
	v_mov_b64_e32 v[66:67], 0
	v_mov_b64_e32 v[68:69], 0
	v_mov_b64_e32 v[70:71], 0
	v_mov_b64_e32 v[80:81], 0
	v_mov_b64_e32 v[82:83], 0
	v_mov_b64_e32 v[84:85], 0
	v_mov_b64_e32 v[86:87], 0
	v_mov_b64_e32 v[96:97], 0
	v_mov_b64_e32 v[98:99], 0
	v_mov_b64_e32 v[100:101], 0
	v_mov_b64_e32 v[102:103], 0
	v_mov_b64_e32 v[112:113], 0
	v_mov_b64_e32 v[114:115], 0
	v_mov_b64_e32 v[116:117], 0
	v_mov_b64_e32 v[118:119], 0
	v_mov_b64_e32 v[72:73], 0
	v_mov_b64_e32 v[74:75], 0
	v_mov_b64_e32 v[76:77], 0
	v_mov_b64_e32 v[78:79], 0
	v_mov_b64_e32 v[88:89], 0
	v_mov_b64_e32 v[90:91], 0
	v_mov_b64_e32 v[92:93], 0
	v_mov_b64_e32 v[94:95], 0
	v_mov_b64_e32 v[104:105], 0
	v_mov_b64_e32 v[106:107], 0
	v_mov_b64_e32 v[108:109], 0
	v_mov_b64_e32 v[110:111], 0
	v_mov_b64_e32 v[120:121], 0
	v_mov_b64_e32 v[122:123], 0
	v_mov_b64_e32 v[124:125], 0
	v_mov_b64_e32 v[126:127], 0

.LBB0_402:
	v_mov_b64_e32 v[126:127], 0
	v_mov_b64_e32 v[124:125], 0
	v_mov_b64_e32 v[122:123], 0
	v_mov_b64_e32 v[120:121], 0
	v_mov_b64_e32 v[110:111], 0
	v_mov_b64_e32 v[108:109], 0
	v_mov_b64_e32 v[106:107], 0
	v_mov_b64_e32 v[104:105], 0
	v_mov_b64_e32 v[94:95], 0
	v_mov_b64_e32 v[92:93], 0
	v_mov_b64_e32 v[90:91], 0
	v_mov_b64_e32 v[88:89], 0
	v_mov_b64_e32 v[78:79], 0
	v_mov_b64_e32 v[76:77], 0
	v_mov_b64_e32 v[74:75], 0
	v_mov_b64_e32 v[72:73], 0
	v_mov_b64_e32 v[118:119], 0
	v_mov_b64_e32 v[116:117], 0
	v_mov_b64_e32 v[114:115], 0
	v_mov_b64_e32 v[112:113], 0
	v_mov_b64_e32 v[102:103], 0
	v_mov_b64_e32 v[100:101], 0
	v_mov_b64_e32 v[98:99], 0
	v_mov_b64_e32 v[96:97], 0
	v_mov_b64_e32 v[86:87], 0
	v_mov_b64_e32 v[84:85], 0
	v_mov_b64_e32 v[82:83], 0
	v_mov_b64_e32 v[80:81], 0
	v_mov_b64_e32 v[70:71], 0
	v_mov_b64_e32 v[68:69], 0
	v_mov_b64_e32 v[66:67], 0
	v_mov_b64_e32 v[64:65], 0
	v_mov_b64_e32 v[62:63], 0
	v_mov_b64_e32 v[60:61], 0
	v_mov_b64_e32 v[58:59], 0
	v_mov_b64_e32 v[56:57], 0
	v_mov_b64_e32 v[46:47], 0
	v_mov_b64_e32 v[44:45], 0
	v_mov_b64_e32 v[42:43], 0
	v_mov_b64_e32 v[40:41], 0
	v_mov_b64_e32 v[30:31], 0
	v_mov_b64_e32 v[28:29], 0
	v_mov_b64_e32 v[26:27], 0
	v_mov_b64_e32 v[24:25], 0
	v_mov_b64_e32 v[14:15], 0
	v_mov_b64_e32 v[12:13], 0
	v_mov_b64_e32 v[10:11], 0
	v_mov_b64_e32 v[8:9], 0
	v_mov_b64_e32 v[54:55], 0
	v_mov_b64_e32 v[52:53], 0
	v_mov_b64_e32 v[50:51], 0
	v_mov_b64_e32 v[48:49], 0
	v_mov_b64_e32 v[38:39], 0
	v_mov_b64_e32 v[36:37], 0
	v_mov_b64_e32 v[34:35], 0
	v_mov_b64_e32 v[32:33], 0
	v_mov_b64_e32 v[22:23], 0
	v_mov_b64_e32 v[20:21], 0
	v_mov_b64_e32 v[18:19], 0
	v_mov_b64_e32 v[16:17], 0
	v_mov_b64_e32 v[6:7], 0
	v_mov_b64_e32 v[4:5], 0
	v_mov_b64_e32 v[2:3], 0
	v_mov_b64_e32 v[0:1], 0
	s_and_b64 vcc, exec, s[14:15]
	s_cbranch_vccnz .LBB0_394
	s_branch .LBB0_395

.LBB0_530:
	s_ashr_i32 s17, s16, 31
	s_lshl_b64 s[18:19], s[16:17], 19
	s_add_u32 s18, s39, s18
	s_addc_u32 s19, s40, s19
	s_and_b64 s[20:21], s[2:3], exec
	s_cselect_b32 s17, s19, s25
	s_cselect_b32 s34, s18, s24
	s_ashr_i32 s15, s14, 31
	s_lshl_b64 s[20:21], s[14:15], 19
	s_add_u32 s20, s41, s20
	s_addc_u32 s21, s42, s21
	s_and_b64 s[36:37], s[2:3], exec
	s_cselect_b32 s15, s21, s27
	s_cselect_b32 s35, s20, s26
	s_add_u32 s24, s24, 0x40080
	s_addc_u32 s25, s25, 0
	s_add_u32 s33, s26, 0x100
	v_mov_b64_e32 v[0:1], 0
	s_addc_u32 s56, s27, 0
	s_mov_b32 s57, -2
	v_mov_b64_e32 v[2:3], 0
	v_mov_b64_e32 v[4:5], 0
	v_mov_b64_e32 v[6:7], 0
	v_mov_b64_e32 v[16:17], 0
	v_mov_b64_e32 v[18:19], 0
	v_mov_b64_e32 v[20:21], 0
	v_mov_b64_e32 v[22:23], 0
	v_mov_b64_e32 v[32:33], 0
	v_mov_b64_e32 v[34:35], 0
	v_mov_b64_e32 v[36:37], 0
	v_mov_b64_e32 v[38:39], 0
	v_mov_b64_e32 v[48:49], 0
	v_mov_b64_e32 v[50:51], 0
	v_mov_b64_e32 v[52:53], 0
	v_mov_b64_e32 v[54:55], 0
	v_mov_b64_e32 v[8:9], 0
	v_mov_b64_e32 v[10:11], 0
	v_mov_b64_e32 v[12:13], 0
	v_mov_b64_e32 v[14:15], 0
	v_mov_b64_e32 v[24:25], 0
	v_mov_b64_e32 v[26:27], 0
	v_mov_b64_e32 v[28:29], 0
	v_mov_b64_e32 v[30:31], 0
	v_mov_b64_e32 v[40:41], 0
	v_mov_b64_e32 v[42:43], 0
	v_mov_b64_e32 v[44:45], 0
	v_mov_b64_e32 v[46:47], 0
	v_mov_b64_e32 v[56:57], 0
	v_mov_b64_e32 v[58:59], 0
	v_mov_b64_e32 v[60:61], 0
	v_mov_b64_e32 v[62:63], 0
	v_mov_b64_e32 v[64:65], 0
	v_mov_b64_e32 v[66:67], 0
	v_mov_b64_e32 v[68:69], 0
	v_mov_b64_e32 v[70:71], 0
	v_mov_b64_e32 v[80:81], 0
	v_mov_b64_e32 v[82:83], 0
	v_mov_b64_e32 v[84:85], 0
	v_mov_b64_e32 v[86:87], 0
	v_mov_b64_e32 v[96:97], 0
	v_mov_b64_e32 v[98:99], 0
	v_mov_b64_e32 v[100:101], 0
	v_mov_b64_e32 v[102:103], 0
	v_mov_b64_e32 v[112:113], 0
	v_mov_b64_e32 v[114:115], 0
	v_mov_b64_e32 v[116:117], 0
	v_mov_b64_e32 v[118:119], 0
	v_mov_b64_e32 v[72:73], 0
	v_mov_b64_e32 v[74:75], 0
	v_mov_b64_e32 v[76:77], 0
	v_mov_b64_e32 v[78:79], 0
	v_mov_b64_e32 v[88:89], 0
	v_mov_b64_e32 v[90:91], 0
	v_mov_b64_e32 v[92:93], 0
	v_mov_b64_e32 v[94:95], 0
	v_mov_b64_e32 v[104:105], 0
	v_mov_b64_e32 v[106:107], 0
	v_mov_b64_e32 v[108:109], 0
	v_mov_b64_e32 v[110:111], 0
	v_mov_b64_e32 v[120:121], 0
	v_mov_b64_e32 v[122:123], 0
	v_mov_b64_e32 v[124:125], 0
	v_mov_b64_e32 v[126:127], 0

.LBB0_609:
	s_cmp_lg_u32 s33, 0
	s_cselect_b64 s[46:47], -1, 0
	s_and_b64 s[34:35], s[46:47], exec
	s_cselect_b32 s34, s33, 44
	s_cmp_lt_i32 s34, 1
	s_cbranch_scc1 .LBB0_621
	s_add_i32 s33, s34, -2
	s_add_u32 s35, s50, 0x100
	v_mov_b64_e32 v[0:1], 0
	s_addc_u32 s91, s51, 0
	s_mov_b32 s52, 0
	v_mov_b64_e32 v[2:3], 0
	v_mov_b64_e32 v[4:5], 0
	v_mov_b64_e32 v[6:7], 0
	v_mov_b64_e32 v[16:17], 0
	v_mov_b64_e32 v[18:19], 0
	v_mov_b64_e32 v[20:21], 0
	v_mov_b64_e32 v[22:23], 0
	v_mov_b64_e32 v[32:33], 0
	v_mov_b64_e32 v[34:35], 0
	v_mov_b64_e32 v[36:37], 0
	v_mov_b64_e32 v[38:39], 0
	v_mov_b64_e32 v[48:49], 0
	v_mov_b64_e32 v[50:51], 0
	v_mov_b64_e32 v[52:53], 0
	v_mov_b64_e32 v[54:55], 0
	v_mov_b64_e32 v[8:9], 0
	v_mov_b64_e32 v[10:11], 0
	v_mov_b64_e32 v[12:13], 0
	v_mov_b64_e32 v[14:15], 0
	v_mov_b64_e32 v[24:25], 0
	v_mov_b64_e32 v[26:27], 0
	v_mov_b64_e32 v[28:29], 0
	v_mov_b64_e32 v[30:31], 0
	v_mov_b64_e32 v[40:41], 0
	v_mov_b64_e32 v[42:43], 0
	v_mov_b64_e32 v[44:45], 0
	v_mov_b64_e32 v[46:47], 0
	v_mov_b64_e32 v[56:57], 0
	v_mov_b64_e32 v[58:59], 0
	v_mov_b64_e32 v[60:61], 0
	v_mov_b64_e32 v[62:63], 0
	v_mov_b64_e32 v[64:65], 0
	v_mov_b64_e32 v[66:67], 0
	v_mov_b64_e32 v[68:69], 0
	v_mov_b64_e32 v[70:71], 0
	v_mov_b64_e32 v[80:81], 0
	v_mov_b64_e32 v[82:83], 0
	v_mov_b64_e32 v[84:85], 0
	v_mov_b64_e32 v[86:87], 0
	v_mov_b64_e32 v[96:97], 0
	v_mov_b64_e32 v[98:99], 0
	v_mov_b64_e32 v[100:101], 0
	v_mov_b64_e32 v[102:103], 0
	v_mov_b64_e32 v[112:113], 0
	v_mov_b64_e32 v[114:115], 0
	v_mov_b64_e32 v[116:117], 0
	v_mov_b64_e32 v[118:119], 0
	v_mov_b64_e32 v[72:73], 0
	v_mov_b64_e32 v[74:75], 0
	v_mov_b64_e32 v[76:77], 0
	v_mov_b64_e32 v[78:79], 0
	v_mov_b64_e32 v[88:89], 0
	v_mov_b64_e32 v[90:91], 0
	v_mov_b64_e32 v[92:93], 0
	v_mov_b64_e32 v[94:95], 0
	v_mov_b64_e32 v[104:105], 0
	v_mov_b64_e32 v[106:107], 0
	v_mov_b64_e32 v[108:109], 0
	v_mov_b64_e32 v[110:111], 0
	v_mov_b64_e32 v[120:121], 0
	v_mov_b64_e32 v[122:123], 0
	v_mov_b64_e32 v[124:125], 0
	v_mov_b64_e32 v[126:127], 0

.LBB0_621:
	v_mov_b64_e32 v[126:127], 0
	v_mov_b64_e32 v[124:125], 0
	v_mov_b64_e32 v[122:123], 0
	v_mov_b64_e32 v[120:121], 0
	v_mov_b64_e32 v[110:111], 0
	v_mov_b64_e32 v[108:109], 0
	v_mov_b64_e32 v[106:107], 0
	v_mov_b64_e32 v[104:105], 0
	v_mov_b64_e32 v[94:95], 0
	v_mov_b64_e32 v[92:93], 0
	v_mov_b64_e32 v[90:91], 0
	v_mov_b64_e32 v[88:89], 0
	v_mov_b64_e32 v[78:79], 0
	v_mov_b64_e32 v[76:77], 0
	v_mov_b64_e32 v[74:75], 0
	v_mov_b64_e32 v[72:73], 0
	v_mov_b64_e32 v[118:119], 0
	v_mov_b64_e32 v[116:117], 0
	v_mov_b64_e32 v[114:115], 0
	v_mov_b64_e32 v[112:113], 0
	v_mov_b64_e32 v[102:103], 0
	v_mov_b64_e32 v[100:101], 0
	v_mov_b64_e32 v[98:99], 0
	v_mov_b64_e32 v[96:97], 0
	v_mov_b64_e32 v[86:87], 0
	v_mov_b64_e32 v[84:85], 0
	v_mov_b64_e32 v[82:83], 0
	v_mov_b64_e32 v[80:81], 0
	v_mov_b64_e32 v[70:71], 0
	v_mov_b64_e32 v[68:69], 0
	v_mov_b64_e32 v[66:67], 0
	v_mov_b64_e32 v[64:65], 0
	v_mov_b64_e32 v[62:63], 0
	v_mov_b64_e32 v[60:61], 0
	v_mov_b64_e32 v[58:59], 0
	v_mov_b64_e32 v[56:57], 0
	v_mov_b64_e32 v[46:47], 0
	v_mov_b64_e32 v[44:45], 0
	v_mov_b64_e32 v[42:43], 0
	v_mov_b64_e32 v[40:41], 0
	v_mov_b64_e32 v[30:31], 0
	v_mov_b64_e32 v[28:29], 0
	v_mov_b64_e32 v[26:27], 0
	v_mov_b64_e32 v[24:25], 0
	v_mov_b64_e32 v[14:15], 0
	v_mov_b64_e32 v[12:13], 0
	v_mov_b64_e32 v[10:11], 0
	v_mov_b64_e32 v[8:9], 0
	v_mov_b64_e32 v[54:55], 0
	v_mov_b64_e32 v[52:53], 0
	v_mov_b64_e32 v[50:51], 0
	v_mov_b64_e32 v[48:49], 0
	v_mov_b64_e32 v[38:39], 0
	v_mov_b64_e32 v[36:37], 0
	v_mov_b64_e32 v[34:35], 0
	v_mov_b64_e32 v[32:33], 0
	v_mov_b64_e32 v[22:23], 0
	v_mov_b64_e32 v[20:21], 0
	v_mov_b64_e32 v[18:19], 0
	v_mov_b64_e32 v[16:17], 0
	v_mov_b64_e32 v[6:7], 0
	v_mov_b64_e32 v[4:5], 0
	v_mov_b64_e32 v[2:3], 0
	v_mov_b64_e32 v[0:1], 0
	s_and_b64 vcc, exec, s[16:17]
	s_cbranch_vccnz .LBB0_613
	s_branch .LBB0_614

.LBB0_747:
	s_ashr_i32 s39, s38, 31
	s_lshl_b64 s[34:35], s[38:39], 19
	s_add_u32 s40, s51, s34
	s_addc_u32 s41, s52, s35
	s_and_b64 s[34:35], s[2:3], exec
	s_cselect_b32 s5, s41, s45
	s_cselect_b32 s34, s40, s44
	s_ashr_i32 s37, s36, 31
	s_lshl_b64 s[42:43], s[36:37], 19
	s_add_u32 s42, s53, s42
	s_addc_u32 s43, s54, s43
	s_and_b64 s[48:49], s[2:3], exec
	s_cselect_b32 s35, s43, s47
	s_cselect_b32 s37, s42, s46
	s_add_u32 s44, s44, 0x40080
	s_addc_u32 s45, s45, 0
	s_add_u32 s33, s46, 0x100
	v_mov_b64_e32 v[0:1], 0
	s_addc_u32 s39, s47, 0
	s_mov_b32 s75, -2
	v_mov_b64_e32 v[2:3], 0
	v_mov_b64_e32 v[4:5], 0
	v_mov_b64_e32 v[6:7], 0
	v_mov_b64_e32 v[16:17], 0
	v_mov_b64_e32 v[18:19], 0
	v_mov_b64_e32 v[20:21], 0
	v_mov_b64_e32 v[22:23], 0
	v_mov_b64_e32 v[32:33], 0
	v_mov_b64_e32 v[34:35], 0
	v_mov_b64_e32 v[36:37], 0
	v_mov_b64_e32 v[38:39], 0
	v_mov_b64_e32 v[48:49], 0
	v_mov_b64_e32 v[50:51], 0
	v_mov_b64_e32 v[52:53], 0
	v_mov_b64_e32 v[54:55], 0
	v_mov_b64_e32 v[8:9], 0
	v_mov_b64_e32 v[10:11], 0
	v_mov_b64_e32 v[12:13], 0
	v_mov_b64_e32 v[14:15], 0
	v_mov_b64_e32 v[24:25], 0
	v_mov_b64_e32 v[26:27], 0
	v_mov_b64_e32 v[28:29], 0
	v_mov_b64_e32 v[30:31], 0
	v_mov_b64_e32 v[40:41], 0
	v_mov_b64_e32 v[42:43], 0
	v_mov_b64_e32 v[44:45], 0
	v_mov_b64_e32 v[46:47], 0
	v_mov_b64_e32 v[56:57], 0
	v_mov_b64_e32 v[58:59], 0
	v_mov_b64_e32 v[60:61], 0
	v_mov_b64_e32 v[62:63], 0
	v_mov_b64_e32 v[64:65], 0
	v_mov_b64_e32 v[66:67], 0
	v_mov_b64_e32 v[68:69], 0
	v_mov_b64_e32 v[70:71], 0
	v_mov_b64_e32 v[80:81], 0
	v_mov_b64_e32 v[82:83], 0
	v_mov_b64_e32 v[84:85], 0
	v_mov_b64_e32 v[86:87], 0
	v_mov_b64_e32 v[96:97], 0
	v_mov_b64_e32 v[98:99], 0
	v_mov_b64_e32 v[100:101], 0
	v_mov_b64_e32 v[102:103], 0
	v_mov_b64_e32 v[112:113], 0
	v_mov_b64_e32 v[114:115], 0
	v_mov_b64_e32 v[116:117], 0
	v_mov_b64_e32 v[118:119], 0
	v_mov_b64_e32 v[72:73], 0
	v_mov_b64_e32 v[74:75], 0
	v_mov_b64_e32 v[76:77], 0
	v_mov_b64_e32 v[78:79], 0
	v_mov_b64_e32 v[88:89], 0
	v_mov_b64_e32 v[90:91], 0
	v_mov_b64_e32 v[92:93], 0
	v_mov_b64_e32 v[94:95], 0
	v_mov_b64_e32 v[104:105], 0
	v_mov_b64_e32 v[106:107], 0
	v_mov_b64_e32 v[108:109], 0
	v_mov_b64_e32 v[110:111], 0
	v_mov_b64_e32 v[120:121], 0
	v_mov_b64_e32 v[122:123], 0
	v_mov_b64_e32 v[124:125], 0
	v_mov_b64_e32 v[126:127], 0

.LBB0_1114:
	s_cmp_lg_u32 s33, 0
	s_cselect_b64 s[54:55], -1, 0
	s_and_b64 s[34:35], s[54:55], exec
	s_cselect_b32 s19, s33, 16
	s_cmp_lt_i32 s19, 1
	s_cbranch_scc1 .LBB0_1126
	s_add_i32 s34, s19, -2
	s_add_u32 s56, s56, 0x40080
	s_addc_u32 s57, s57, 0
	s_add_u32 s33, s58, 0x100
	v_mov_b64_e32 v[0:1], 0
	s_addc_u32 s35, s59, 0
	s_mov_b32 s47, 0
	v_mov_b64_e32 v[2:3], 0
	v_mov_b64_e32 v[4:5], 0
	v_mov_b64_e32 v[6:7], 0
	v_mov_b64_e32 v[16:17], 0
	v_mov_b64_e32 v[18:19], 0
	v_mov_b64_e32 v[20:21], 0
	v_mov_b64_e32 v[22:23], 0
	v_mov_b64_e32 v[32:33], 0
	v_mov_b64_e32 v[34:35], 0
	v_mov_b64_e32 v[36:37], 0
	v_mov_b64_e32 v[38:39], 0
	v_mov_b64_e32 v[48:49], 0
	v_mov_b64_e32 v[50:51], 0
	v_mov_b64_e32 v[52:53], 0
	v_mov_b64_e32 v[54:55], 0
	v_mov_b64_e32 v[8:9], 0
	v_mov_b64_e32 v[10:11], 0
	v_mov_b64_e32 v[12:13], 0
	v_mov_b64_e32 v[14:15], 0
	v_mov_b64_e32 v[24:25], 0
	v_mov_b64_e32 v[26:27], 0
	v_mov_b64_e32 v[28:29], 0
	v_mov_b64_e32 v[30:31], 0
	v_mov_b64_e32 v[40:41], 0
	v_mov_b64_e32 v[42:43], 0
	v_mov_b64_e32 v[44:45], 0
	v_mov_b64_e32 v[46:47], 0
	v_mov_b64_e32 v[56:57], 0
	v_mov_b64_e32 v[58:59], 0
	v_mov_b64_e32 v[60:61], 0
	v_mov_b64_e32 v[62:63], 0
	v_mov_b64_e32 v[64:65], 0
	v_mov_b64_e32 v[66:67], 0
	v_mov_b64_e32 v[68:69], 0
	v_mov_b64_e32 v[70:71], 0
	v_mov_b64_e32 v[80:81], 0
	v_mov_b64_e32 v[82:83], 0
	v_mov_b64_e32 v[84:85], 0
	v_mov_b64_e32 v[86:87], 0
	v_mov_b64_e32 v[96:97], 0
	v_mov_b64_e32 v[98:99], 0
	v_mov_b64_e32 v[100:101], 0
	v_mov_b64_e32 v[102:103], 0
	v_mov_b64_e32 v[112:113], 0
	v_mov_b64_e32 v[114:115], 0
	v_mov_b64_e32 v[116:117], 0
	v_mov_b64_e32 v[118:119], 0
	v_mov_b64_e32 v[72:73], 0
	v_mov_b64_e32 v[74:75], 0
	v_mov_b64_e32 v[76:77], 0
	v_mov_b64_e32 v[78:79], 0
	v_mov_b64_e32 v[88:89], 0
	v_mov_b64_e32 v[90:91], 0
	v_mov_b64_e32 v[92:93], 0
	v_mov_b64_e32 v[94:95], 0
	v_mov_b64_e32 v[104:105], 0
	v_mov_b64_e32 v[106:107], 0
	v_mov_b64_e32 v[108:109], 0
	v_mov_b64_e32 v[110:111], 0
	v_mov_b64_e32 v[120:121], 0
	v_mov_b64_e32 v[122:123], 0
	v_mov_b64_e32 v[124:125], 0
	v_mov_b64_e32 v[126:127], 0

.LBB0_1471:
	s_ashr_i32 s41, s40, 31
	s_lshl_b64 s[10:11], s[40:41], 19
	s_add_u32 s42, s51, s10
	s_addc_u32 s43, s52, s11
	s_and_b64 s[10:11], s[2:3], exec
	s_cselect_b32 s5, s43, s7
	s_cselect_b32 s13, s42, s6
	s_ashr_i32 s39, s38, 31
	s_lshl_b64 s[10:11], s[38:39], 19
	s_add_u32 s44, s53, s10
	s_addc_u32 s45, s54, s11
	s_and_b64 s[10:11], s[2:3], exec
	s_cselect_b32 s16, s45, s9
	s_cselect_b32 s34, s44, s8
	s_add_u32 s6, s6, 0x40080
	s_addc_u32 s7, s7, 0
	s_add_u32 s33, s8, 0x100
	v_mov_b64_e32 v[0:1], 0
	s_addc_u32 s35, s9, 0
	s_mov_b32 s39, -2
	v_mov_b64_e32 v[2:3], 0
	v_mov_b64_e32 v[4:5], 0
	v_mov_b64_e32 v[6:7], 0
	v_mov_b64_e32 v[16:17], 0
	v_mov_b64_e32 v[18:19], 0
	v_mov_b64_e32 v[20:21], 0
	v_mov_b64_e32 v[22:23], 0
	v_mov_b64_e32 v[32:33], 0
	v_mov_b64_e32 v[34:35], 0
	v_mov_b64_e32 v[36:37], 0
	v_mov_b64_e32 v[38:39], 0
	v_mov_b64_e32 v[48:49], 0
	v_mov_b64_e32 v[50:51], 0
	v_mov_b64_e32 v[52:53], 0
	v_mov_b64_e32 v[54:55], 0
	v_mov_b64_e32 v[8:9], 0
	v_mov_b64_e32 v[10:11], 0
	v_mov_b64_e32 v[12:13], 0
	v_mov_b64_e32 v[14:15], 0
	v_mov_b64_e32 v[24:25], 0
	v_mov_b64_e32 v[26:27], 0
	v_mov_b64_e32 v[28:29], 0
	v_mov_b64_e32 v[30:31], 0
	v_mov_b64_e32 v[40:41], 0
	v_mov_b64_e32 v[42:43], 0
	v_mov_b64_e32 v[44:45], 0
	v_mov_b64_e32 v[46:47], 0
	v_mov_b64_e32 v[56:57], 0
	v_mov_b64_e32 v[58:59], 0
	v_mov_b64_e32 v[60:61], 0
	v_mov_b64_e32 v[62:63], 0
	v_mov_b64_e32 v[64:65], 0
	v_mov_b64_e32 v[66:67], 0
	v_mov_b64_e32 v[68:69], 0
	v_mov_b64_e32 v[70:71], 0
	v_mov_b64_e32 v[80:81], 0
	v_mov_b64_e32 v[82:83], 0
	v_mov_b64_e32 v[84:85], 0
	v_mov_b64_e32 v[86:87], 0
	v_mov_b64_e32 v[96:97], 0
	v_mov_b64_e32 v[98:99], 0
	v_mov_b64_e32 v[100:101], 0
	v_mov_b64_e32 v[102:103], 0
	v_mov_b64_e32 v[112:113], 0
	v_mov_b64_e32 v[114:115], 0
	v_mov_b64_e32 v[116:117], 0
	v_mov_b64_e32 v[118:119], 0
	v_mov_b64_e32 v[72:73], 0
	v_mov_b64_e32 v[74:75], 0
	v_mov_b64_e32 v[76:77], 0
	v_mov_b64_e32 v[78:79], 0
	v_mov_b64_e32 v[88:89], 0
	v_mov_b64_e32 v[90:91], 0
	v_mov_b64_e32 v[92:93], 0
	v_mov_b64_e32 v[94:95], 0
	v_mov_b64_e32 v[104:105], 0
	v_mov_b64_e32 v[106:107], 0
	v_mov_b64_e32 v[108:109], 0
	v_mov_b64_e32 v[110:111], 0
	v_mov_b64_e32 v[120:121], 0
	v_mov_b64_e32 v[122:123], 0
	v_mov_b64_e32 v[124:125], 0
	v_mov_b64_e32 v[126:127], 0

.LBB0_1947:
	s_cmp_lg_u32 s33, 0
	s_cselect_b64 s[54:55], -1, 0
	s_and_b64 s[34:35], s[54:55], exec
	s_cselect_b32 s19, s33, 32
	s_cmp_lt_i32 s19, 1
	s_cbranch_scc1 .LBB0_1959
	s_add_i32 s34, s19, -2
	s_add_u32 s56, s56, 0x80080
	s_addc_u32 s57, s57, 0
	s_add_u32 s33, s58, 0x100
	v_mov_b64_e32 v[0:1], 0
	s_addc_u32 s35, s59, 0
	s_mov_b32 s47, 0
	v_mov_b64_e32 v[2:3], 0
	v_mov_b64_e32 v[4:5], 0
	v_mov_b64_e32 v[6:7], 0
	v_mov_b64_e32 v[16:17], 0
	v_mov_b64_e32 v[18:19], 0
	v_mov_b64_e32 v[20:21], 0
	v_mov_b64_e32 v[22:23], 0
	v_mov_b64_e32 v[32:33], 0
	v_mov_b64_e32 v[34:35], 0
	v_mov_b64_e32 v[36:37], 0
	v_mov_b64_e32 v[38:39], 0
	v_mov_b64_e32 v[48:49], 0
	v_mov_b64_e32 v[50:51], 0
	v_mov_b64_e32 v[52:53], 0
	v_mov_b64_e32 v[54:55], 0
	v_mov_b64_e32 v[8:9], 0
	v_mov_b64_e32 v[10:11], 0
	v_mov_b64_e32 v[12:13], 0
	v_mov_b64_e32 v[14:15], 0
	v_mov_b64_e32 v[24:25], 0
	v_mov_b64_e32 v[26:27], 0
	v_mov_b64_e32 v[28:29], 0
	v_mov_b64_e32 v[30:31], 0
	v_mov_b64_e32 v[40:41], 0
	v_mov_b64_e32 v[42:43], 0
	v_mov_b64_e32 v[44:45], 0
	v_mov_b64_e32 v[46:47], 0
	v_mov_b64_e32 v[56:57], 0
	v_mov_b64_e32 v[58:59], 0
	v_mov_b64_e32 v[60:61], 0
	v_mov_b64_e32 v[62:63], 0
	v_mov_b64_e32 v[64:65], 0
	v_mov_b64_e32 v[66:67], 0
	v_mov_b64_e32 v[68:69], 0
	v_mov_b64_e32 v[70:71], 0
	v_mov_b64_e32 v[80:81], 0
	v_mov_b64_e32 v[82:83], 0
	v_mov_b64_e32 v[84:85], 0
	v_mov_b64_e32 v[86:87], 0
	v_mov_b64_e32 v[96:97], 0
	v_mov_b64_e32 v[98:99], 0
	v_mov_b64_e32 v[100:101], 0
	v_mov_b64_e32 v[102:103], 0
	v_mov_b64_e32 v[112:113], 0
	v_mov_b64_e32 v[114:115], 0
	v_mov_b64_e32 v[116:117], 0
	v_mov_b64_e32 v[118:119], 0
	v_mov_b64_e32 v[72:73], 0
	v_mov_b64_e32 v[74:75], 0
	v_mov_b64_e32 v[76:77], 0
	v_mov_b64_e32 v[78:79], 0
	v_mov_b64_e32 v[88:89], 0
	v_mov_b64_e32 v[90:91], 0
	v_mov_b64_e32 v[92:93], 0
	v_mov_b64_e32 v[94:95], 0
	v_mov_b64_e32 v[104:105], 0
	v_mov_b64_e32 v[106:107], 0
	v_mov_b64_e32 v[108:109], 0
	v_mov_b64_e32 v[110:111], 0
	v_mov_b64_e32 v[120:121], 0
	v_mov_b64_e32 v[122:123], 0
	v_mov_b64_e32 v[124:125], 0
	v_mov_b64_e32 v[126:127], 0

.LBB0_2304:
	s_ashr_i32 s59, s58, 31
	s_lshl_b64 s[34:35], s[58:59], 19
	s_add_u32 s60, s41, s34
	s_addc_u32 s61, s43, s35
	s_and_b64 s[34:35], s[4:5], exec
	s_cselect_b32 s9, s61, s7
	s_cselect_b32 s34, s60, s6
	s_ashr_i32 s57, s56, 31
	s_lshl_b64 s[62:63], s[56:57], 19
	s_add_u32 s62, s45, s62
	s_addc_u32 s63, s47, s63
	s_and_b64 s[68:69], s[4:5], exec
	s_cselect_b32 s35, s63, s67
	s_cselect_b32 s57, s62, s66
	s_add_u32 s6, s6, 0x40080
	s_addc_u32 s7, s7, 0
	s_add_u32 s33, s66, 0x100
	v_mov_b64_e32 v[0:1], 0
	s_addc_u32 s59, s67, 0
	s_mov_b32 s96, -2
	v_mov_b64_e32 v[2:3], 0
	v_mov_b64_e32 v[4:5], 0
	v_mov_b64_e32 v[6:7], 0
	v_mov_b64_e32 v[16:17], 0
	v_mov_b64_e32 v[18:19], 0
	v_mov_b64_e32 v[20:21], 0
	v_mov_b64_e32 v[22:23], 0
	v_mov_b64_e32 v[32:33], 0
	v_mov_b64_e32 v[34:35], 0
	v_mov_b64_e32 v[36:37], 0
	v_mov_b64_e32 v[38:39], 0
	v_mov_b64_e32 v[48:49], 0
	v_mov_b64_e32 v[50:51], 0
	v_mov_b64_e32 v[52:53], 0
	v_mov_b64_e32 v[54:55], 0
	v_mov_b64_e32 v[8:9], 0
	v_mov_b64_e32 v[10:11], 0
	v_mov_b64_e32 v[12:13], 0
	v_mov_b64_e32 v[14:15], 0
	v_mov_b64_e32 v[24:25], 0
	v_mov_b64_e32 v[26:27], 0
	v_mov_b64_e32 v[28:29], 0
	v_mov_b64_e32 v[30:31], 0
	v_mov_b64_e32 v[40:41], 0
	v_mov_b64_e32 v[42:43], 0
	v_mov_b64_e32 v[44:45], 0
	v_mov_b64_e32 v[46:47], 0
	v_mov_b64_e32 v[56:57], 0
	v_mov_b64_e32 v[58:59], 0
	v_mov_b64_e32 v[60:61], 0
	v_mov_b64_e32 v[62:63], 0
	v_mov_b64_e32 v[64:65], 0
	v_mov_b64_e32 v[66:67], 0
	v_mov_b64_e32 v[68:69], 0
	v_mov_b64_e32 v[70:71], 0
	v_mov_b64_e32 v[80:81], 0
	v_mov_b64_e32 v[82:83], 0
	v_mov_b64_e32 v[84:85], 0
	v_mov_b64_e32 v[86:87], 0
	v_mov_b64_e32 v[96:97], 0
	v_mov_b64_e32 v[98:99], 0
	v_mov_b64_e32 v[100:101], 0
	v_mov_b64_e32 v[102:103], 0
	v_mov_b64_e32 v[112:113], 0
	v_mov_b64_e32 v[114:115], 0
	v_mov_b64_e32 v[116:117], 0
	v_mov_b64_e32 v[118:119], 0
	v_mov_b64_e32 v[72:73], 0
	v_mov_b64_e32 v[74:75], 0
	v_mov_b64_e32 v[76:77], 0
	v_mov_b64_e32 v[78:79], 0
	v_mov_b64_e32 v[88:89], 0
	v_mov_b64_e32 v[90:91], 0
	v_mov_b64_e32 v[92:93], 0
	v_mov_b64_e32 v[94:95], 0
	v_mov_b64_e32 v[104:105], 0
	v_mov_b64_e32 v[106:107], 0
	v_mov_b64_e32 v[108:109], 0
	v_mov_b64_e32 v[110:111], 0
	v_mov_b64_e32 v[120:121], 0
	v_mov_b64_e32 v[122:123], 0
	v_mov_b64_e32 v[124:125], 0
	v_mov_b64_e32 v[126:127], 0
